# P5/P6 start stagger: odd XCDs 0.75 us late
# baseline (speedup 1.0000x reference)
; #define LAS __attribute__((address_space(3)))
;     DI bool next(int i, Unit& u) const {
;         const long L = (long)i * G + c; if (L >= nwg) return false;
;         int wgid = (int)L; { const int q = nwg / NXCD, r = nwg % NXCD, xcd = wgid % NXCD, off = wgid / NXCD; wgid = (xcd < r ? xcd * (q + 1) : r * (q + 1) + (xcd - r) * q) + off; }
;         const int nig = WGM * nN, gid = wgid / nig, fm = gid * WGM, gsz = (nM - fm) < WGM ? (nM - fm) : WGM;
;         u.pm = fm + ((wgid % nig) % gsz); u.pn = (wgid % nig) / gsz; return true;
; __global__ void __launch_bounds__(512, 2) mega(Params p) {
;     ...
;     if (PH(5)) {
;         pg8::Gemm g; g.A0 = (const bf16_t*)(p.ws + WS_ZG); g.A1 = (const bf16_t*)(p.ws + WS_YB) - 2048; g.B0 = (const bf16_t*)(p.ws + WS_WAT); g.B1 = (const bf16_t*)(p.ws + WS_WBT) - 2048;
;         g.lda = DM; g.ldb = DM; g.M = S; g.N = DM; g.K = 2 * DM; g.ksplit = DM / 64;
;         pg8::StaticOrder so; so.init(g.M, g.N, (int)gridDim.x, (int)blockIdx.x);
;         EpiMergeMid e; e.ws = p.ws;
;         pg8::gemm_phase<EpiMergeMid>((LAS unsigned char*)shm, g, so, e);
.LBB0_431:
	s_or_b64 exec, exec, s[4:5]
	v_cmp_gt_i32_e32 vcc, 6, v0
	v_cmp_lt_i32_e64 s[4:5], 5, v1
	s_and_b64 s[4:5], vcc, s[4:5]
	s_and_saveexec_b64 s[6:7], s[4:5]
	s_cbranch_execz .LBB0_456
	s_bitcmp1_b32 s2, 0
	s_cbranch_scc0 .Lp5_nostag
	s_sleep 20

; #define LAS __attribute__((address_space(3)))
;     DI bool next(int i, Unit& u) const {
;         const long L = (long)i * G + c; if (L >= nwg) return false;
;         int wgid = (int)L; { const int q = nwg / NXCD, r = nwg % NXCD, xcd = wgid % NXCD, off = wgid / NXCD; wgid = (xcd < r ? xcd * (q + 1) : r * (q + 1) + (xcd - r) * q) + off; }
;         const int nig = WGM * nN, gid = wgid / nig, fm = gid * WGM, gsz = (nM - fm) < WGM ? (nM - fm) : WGM;
;         u.pm = fm + ((wgid % nig) % gsz); u.pn = (wgid % nig) / gsz; return true;
; __global__ void __launch_bounds__(512, 2) mega(Params p) {
;     ...
;     if (PH(6)) {
;         pg8::Gemm g; g.A0 = (const bf16_t*)(p.ws + WS_MRG); g.A1 = g.A0; g.B0 = (const bf16_t*)(p.ws + WS_WOT); g.B1 = g.B0;
;         g.lda = DM; g.ldb = DM; g.M = S; g.N = DM; g.K = DM; g.ksplit = DM / 64;
;         pg8::StaticOrder so; so.init(g.M, g.N, (int)gridDim.x, (int)blockIdx.x);
;         EpiOut e; e.ws = p.ws;
;         pg8::gemm_phase<EpiOut>((LAS unsigned char*)shm, g, so, e);
.LBB0_506:
	s_or_b64 exec, exec, s[4:5]
	v_cmp_gt_i32_e32 vcc, 7, v0
	v_cmp_lt_i32_e64 s[4:5], 6, v1
	s_and_b64 s[4:5], vcc, s[4:5]
	s_and_saveexec_b64 s[8:9], s[4:5]
	s_cbranch_execz .LBB0_545
	s_bitcmp1_b32 s2, 0
	s_cbranch_scc0 .Lp6_nostag
	s_sleep 20
